# sample loop: s1 scan and s2 dot-product reductions via DPP, s6 RED reads and s7 kd^T fragment reads issued in one batch; on top of v14
# baseline (speedup 1.0000x reference)
.LBB0_1058:
	v_mov_b32_e32 v100, v129
	s_add_i32 s2, s25, s30
	v_readlane_b32 s40, v248, 13
	s_ashr_i32 s3, s2, 31
	v_and_b32_e32 v155, 15, v100
	v_readlane_b32 s44, v248, 17
	v_readlane_b32 s45, v248, 18
	v_readlane_b32 s48, v248, 21
	v_readlane_b32 s49, v248, 22
	v_ashrrev_i32_e32 v158, 6, v100
	v_cvt_pk_bf16_f32 v101, v60, s0
	v_lshlrev_b32_e32 v156, 7, v155
	s_lshl_b64 s[0:1], s[2:3], 16
	s_mov_b64 s[44:45], s[48:49]
	v_lshlrev_b32_e32 v118, 4, v158
	s_add_u32 s0, s44, s0
	v_or_b32_e32 v68, 0x800, v156
	v_ashrrev_i32_e32 v119, 31, v118
	s_addc_u32 s1, s45, s1
	v_lshlrev_b32_e32 v104, 9, v155
	v_lshlrev_b32_e32 v122, 2, v68
	v_mov_b32_e32 v123, v105
	v_lshl_add_u64 v[64:65], s[0:1], 0, v[104:105]
	v_lshlrev_b64 v[66:67], 2, v[118:119]
	v_lshl_add_u64 v[68:69], s[0:1], 0, v[122:123]
	v_lshl_add_u64 v[64:65], v[64:65], 0, v[66:67]
	v_and_b32_e32 v96, 48, v100
	v_mov_b32_e32 v97, v105
	v_lshl_add_u64 v[68:69], v[68:69], 0, v[66:67]
	v_lshl_add_u64 v[64:65], v[64:65], 0, v[96:97]
	v_lshl_add_u64 v[68:69], v[68:69], 0, v[96:97]
	global_load_dwordx4 v[92:95], v[64:65], off
	global_load_dwordx4 v[88:91], v[68:69], off
	v_or_b32_e32 v64, 0x1000, v156
	v_or_b32_e32 v68, 0x1800, v156
	v_lshlrev_b32_e32 v120, 2, v64
	v_mov_b32_e32 v121, v105
	v_lshlrev_b32_e32 v116, 2, v68
	v_mov_b32_e32 v117, v105
	v_lshl_add_u64 v[64:65], s[0:1], 0, v[120:121]
	v_lshl_add_u64 v[68:69], s[0:1], 0, v[116:117]
	v_lshl_add_u64 v[64:65], v[64:65], 0, v[66:67]
	v_lshl_add_u64 v[68:69], v[68:69], 0, v[66:67]
	v_lshl_add_u64 v[64:65], v[64:65], 0, v[96:97]
	v_lshl_add_u64 v[68:69], v[68:69], 0, v[96:97]
	global_load_dwordx4 v[84:87], v[64:65], off
	global_load_dwordx4 v[80:83], v[68:69], off
	v_or_b32_e32 v64, 0x2000, v156
	v_or_b32_e32 v68, 0x2800, v156
	v_lshlrev_b32_e32 v114, 2, v64
	v_mov_b32_e32 v115, v105
	v_lshlrev_b32_e32 v112, 2, v68
	v_mov_b32_e32 v113, v105
	v_lshl_add_u64 v[64:65], s[0:1], 0, v[114:115]
	v_lshl_add_u64 v[68:69], s[0:1], 0, v[112:113]
	v_lshl_add_u64 v[64:65], v[64:65], 0, v[66:67]
	v_lshl_add_u64 v[68:69], v[68:69], 0, v[66:67]
	v_lshl_add_u64 v[64:65], v[64:65], 0, v[96:97]
	v_lshl_add_u64 v[68:69], v[68:69], 0, v[96:97]
	global_load_dwordx4 v[76:79], v[64:65], off
	global_load_dwordx4 v[72:75], v[68:69], off
	v_or_b32_e32 v64, 0x3000, v156
	v_or_b32_e32 v68, 0x3800, v156
	v_lshlrev_b32_e32 v110, 2, v64
	v_mov_b32_e32 v111, v105
	v_lshlrev_b32_e32 v108, 2, v68
	v_mov_b32_e32 v109, v105
	v_lshl_add_u64 v[64:65], s[0:1], 0, v[110:111]
	v_lshl_add_u64 v[68:69], s[0:1], 0, v[108:109]
	v_lshl_add_u64 v[64:65], v[64:65], 0, v[66:67]
	v_lshl_add_u64 v[66:67], v[68:69], 0, v[66:67]
	v_lshl_add_u64 v[64:65], v[64:65], 0, v[96:97]
	v_lshl_add_u64 v[66:67], v[66:67], 0, v[96:97]
	global_load_dwordx4 v[68:71], v[64:65], off
	s_nop 0
	global_load_dwordx4 v[64:67], v[66:67], off
	v_bfe_u32 v159, v100, 4, 2
	v_lshlrev_b32_e32 v154, 2, v159
	v_or_b32_e32 v99, v154, v118
	v_lshlrev_b32_e32 v98, 1, v155
	v_mul_lo_u32 v97, v99, s27
	v_add3_u32 v97, 0, v98, v97
	v_cvt_pk_bf16_f32 v99, v61, s0
	ds_write_b16 v97, v99 offset:272
	v_cvt_pk_bf16_f32 v99, v62, s0
	ds_write_b16 v97, v99 offset:544
	v_cvt_pk_bf16_f32 v99, v63, s0
	ds_write_b16 v97, v99 offset:816
	v_cvt_pk_bf16_f32 v99, v56, s0
	ds_write_b16 v97, v99 offset:32
	v_cvt_pk_bf16_f32 v99, v57, s0
	ds_write_b16 v97, v99 offset:304
	v_cvt_pk_bf16_f32 v99, v58, s0
	ds_write_b16 v97, v99 offset:576
	v_cvt_pk_bf16_f32 v99, v59, s0
	ds_write_b16 v97, v99 offset:848
	v_cvt_pk_bf16_f32 v99, v52, s0
	ds_write_b16 v97, v99 offset:64
	v_cvt_pk_bf16_f32 v99, v53, s0
	ds_write_b16 v97, v99 offset:336
	v_cvt_pk_bf16_f32 v99, v54, s0
	ds_write_b16 v97, v99 offset:608
	v_cvt_pk_bf16_f32 v99, v55, s0
	ds_write_b16 v97, v99 offset:880
	v_cvt_pk_bf16_f32 v99, v48, s0
	ds_write_b16 v97, v99 offset:96
	v_cvt_pk_bf16_f32 v99, v49, s0
	ds_write_b16 v97, v99 offset:368
	v_cvt_pk_bf16_f32 v99, v50, s0
	ds_write_b16 v97, v99 offset:640
	v_cvt_pk_bf16_f32 v99, v51, s0
	ds_write_b16 v97, v99 offset:912
	v_cvt_pk_bf16_f32 v99, v44, s0
	ds_write_b16 v97, v99 offset:128
	v_cvt_pk_bf16_f32 v99, v45, s0
	ds_write_b16 v97, v99 offset:400
	v_cvt_pk_bf16_f32 v99, v46, s0
	ds_write_b16 v97, v99 offset:672
	v_cvt_pk_bf16_f32 v99, v47, s0
	ds_write_b16 v97, v99 offset:944
	v_cvt_pk_bf16_f32 v99, v40, s0
	ds_write_b16 v97, v99 offset:160
	v_cvt_pk_bf16_f32 v99, v41, s0
	ds_write_b16 v97, v99 offset:432
	v_cvt_pk_bf16_f32 v99, v42, s0
	ds_write_b16 v97, v99 offset:704
	v_cvt_pk_bf16_f32 v99, v43, s0
	ds_write_b16 v97, v99 offset:976
	v_cvt_pk_bf16_f32 v99, v36, s0
	ds_write_b16 v97, v99 offset:192
	v_cvt_pk_bf16_f32 v99, v37, s0
	ds_write_b16 v97, v99 offset:464
	v_cvt_pk_bf16_f32 v99, v38, s0
	ds_write_b16 v97, v99 offset:736
	v_cvt_pk_bf16_f32 v99, v39, s0
	ds_write_b16 v97, v99 offset:1008
	v_cvt_pk_bf16_f32 v99, v32, s0
	ds_write_b16 v97, v99 offset:224
	v_cvt_pk_bf16_f32 v99, v33, s0
	ds_write_b16 v97, v99 offset:496
	v_cvt_pk_bf16_f32 v99, v34, s0
	v_and_b32_e32 v160, 63, v100
	ds_write_b16 v97, v99 offset:768
	v_cvt_pk_bf16_f32 v99, v35, s0
	ds_write_b16 v97, v101
	ds_write_b16 v97, v99 offset:1040
	v_lshlrev_b32_e32 v97, 1, v160
	v_mul_lo_u32 v101, v158, s28
	v_add_u32_e32 v99, v101, v97
	v_lshlrev_b32_e32 v102, 16, v143
	v_lshl_add_u32 v99, v99, 2, 0
	v_and_b32_e32 v103, 0xffff0000, v143
	ds_write_b64 v99, v[102:103] offset:34816
	v_lshlrev_b32_e32 v102, 16, v142
	v_and_b32_e32 v103, 0xffff0000, v142
	ds_write_b64 v99, v[102:103] offset:39168
	v_lshlrev_b32_e32 v102, 16, v141
	v_and_b32_e32 v103, 0xffff0000, v141
	v_cmp_gt_u32_e32 vcc, 64, v100
	v_readlane_b32 s41, v248, 14
	v_readlane_b32 s42, v248, 15
	v_readlane_b32 s43, v248, 16
	v_readlane_b32 s46, v248, 19
	v_readlane_b32 s47, v248, 20
	v_readlane_b32 s50, v248, 23
	v_readlane_b32 s51, v248, 24
	v_readlane_b32 s52, v248, 25
	v_readlane_b32 s53, v248, 26
	v_readlane_b32 s54, v248, 27
	v_readlane_b32 s55, v248, 28
	ds_write_b64 v99, v[102:103] offset:43520
	s_and_saveexec_b64 s[14:15], vcc
	s_cbranch_execz .LBB0_1061
	v_cmp_gt_u32_e32 vcc, 8, v100
	v_cmp_eq_u32_e64 s[0:1], 0, v160
	s_nop 0
	v_cndmask_b32_e32 v99, 0, v140, vcc
	s_nop 1
	v_add_f32_dpp v99, v99, v99 row_shr:1 row_mask:0xf bank_mask:0xf bound_ctrl:0
	s_nop 1
	v_add_f32_dpp v99, v99, v99 row_shr:2 row_mask:0xf bank_mask:0xf bound_ctrl:0
	s_nop 1
	v_add_f32_dpp v99, v99, v99 row_shr:4 row_mask:0xf bank_mask:0xf bound_ctrl:0
	v_cmp_gt_u32_e64 s[0:1], 2, v160
	s_and_b64 exec, exec, vcc
	s_cbranch_execz .LBB0_1061
	v_cmp_gt_u32_e32 vcc, 4, v160
	s_nop 1
	v_lshl_add_u32 v102, v100, 2, 0
	v_add_u32_e32 v102, 0xb800, v102
	ds_write2_b32 v102, v99, v139 offset0:192 offset1:200

.LBB0_1063:
	s_or_b64 exec, exec, s[0:1]
	v_lshlrev_b32_e32 v97, 1, v159
	v_or_b32_e32 v102, s14, v97
	v_ashrrev_i32_e32 v103, 31, v102
	v_lshlrev_b64 v[124:125], 13, v[102:103]
	v_or_b32_e32 v102, 1, v102
	s_lshl_b32 s0, s3, 7
	v_ashrrev_i32_e32 v103, 31, v102
	v_lshl_add_u64 v[124:125], s[10:11], 0, v[124:125]
	s_lshl_b32 s12, s0, 1
	v_lshlrev_b64 v[102:103], 13, v[102:103]
	v_lshl_add_u64 v[124:125], v[124:125], 0, s[12:13]
	v_lshlrev_b64 v[126:127], 1, v[118:119]
	v_lshl_add_u64 v[102:103], s[10:11], 0, v[102:103]
	v_lshl_add_u64 v[124:125], v[124:125], 0, v[126:127]
	v_mov_b32_e32 v99, v105
	v_lshl_add_u64 v[102:103], v[102:103], 0, s[12:13]
	v_lshl_add_u64 v[124:125], v[124:125], 0, v[98:99]
	v_lshl_add_u64 v[102:103], v[102:103], 0, v[126:127]
	v_lshl_add_u64 v[98:99], v[102:103], 0, v[98:99]
	global_load_ushort v109, v[124:125], off
	global_load_ushort v157, v[98:99], off
	v_bfe_u32 v98, v100, 3, 3
	v_and_b32_e32 v104, 7, v100
	v_or_b32_e32 v99, v101, v104
	v_mul_u32_u24_e32 v101, 0x220, v98
	v_lshlrev_b32_e32 v102, 2, v104
	v_add3_u32 v101, 0, v101, v102
	v_lshl_add_u32 v99, v99, 2, 0
	s_waitcnt lgkmcnt(0)
	s_barrier
	v_add_u32_e32 v101, 0x8800, v101
	v_add_u32_e32 v111, 0x8800, v99
	ds_read2_b32 v[102:103], v101 offset1:8
	ds_read2_b32 v[124:125], v111 offset1:8
	v_add_u32_e32 v99, 0x9800, v99
	ds_read2_b32 v[126:127], v99 offset0:64 offset1:72
	ds_read2_b32 v[162:163], v101 offset0:16 offset1:24
	ds_read2_b32 v[164:165], v111 offset0:16 offset1:24
	v_cmp_eq_u32_e64 s[0:1], 0, v104
	s_waitcnt lgkmcnt(3)
	v_fma_f32 v113, v102, v124, 0
	v_fmac_f32_e32 v113, v103, v125
	ds_read2_b32 v[124:125], v99 offset0:80 offset1:88
	s_waitcnt lgkmcnt(3)
	v_fma_f32 v115, v102, v126, 0
	s_waitcnt lgkmcnt(1)
	v_fmac_f32_e32 v113, v162, v164
	v_fmac_f32_e32 v115, v103, v127
	ds_read2_b32 v[102:103], v101 offset0:32 offset1:40
	ds_read2_b32 v[126:127], v111 offset0:32 offset1:40
	v_fmac_f32_e32 v113, v163, v165
	ds_read2_b32 v[164:165], v99 offset0:96 offset1:104
	s_waitcnt lgkmcnt(3)
	v_fmac_f32_e32 v115, v162, v124
	v_fmac_f32_e32 v115, v163, v125
	ds_read2_b32 v[124:125], v101 offset0:48 offset1:56
	ds_read2_b32 v[162:163], v111 offset0:48 offset1:56
	s_waitcnt lgkmcnt(3)
	v_fmac_f32_e32 v113, v102, v126
	s_waitcnt lgkmcnt(2)
	v_fmac_f32_e32 v115, v102, v164
	v_fmac_f32_e32 v113, v103, v127
	ds_read2_b32 v[126:127], v99 offset0:112 offset1:120
	v_fmac_f32_e32 v115, v103, v165
	ds_read2_b32 v[102:103], v101 offset0:64 offset1:72
	ds_read2_b32 v[164:165], v111 offset0:64 offset1:72
	s_waitcnt lgkmcnt(3)
	v_fmac_f32_e32 v113, v124, v162
	v_fmac_f32_e32 v113, v125, v163
	ds_read2_b32 v[162:163], v99 offset0:128 offset1:136
	s_waitcnt lgkmcnt(3)
	v_fmac_f32_e32 v115, v124, v126
	s_waitcnt lgkmcnt(1)
	v_fmac_f32_e32 v113, v102, v164
	v_fmac_f32_e32 v115, v125, v127
	ds_read2_b32 v[124:125], v101 offset0:80 offset1:88
	ds_read2_b32 v[126:127], v111 offset0:80 offset1:88
	v_fmac_f32_e32 v113, v103, v165
	ds_read2_b32 v[164:165], v99 offset0:144 offset1:152
	s_waitcnt lgkmcnt(3)
	v_fmac_f32_e32 v115, v102, v162
	v_fmac_f32_e32 v115, v103, v163
	s_waitcnt lgkmcnt(1)
	v_fmac_f32_e32 v113, v124, v126
	ds_read2_b32 v[102:103], v101 offset0:96 offset1:104
	ds_read2_b32 v[162:163], v111 offset0:96 offset1:104
	s_waitcnt lgkmcnt(2)
	v_fmac_f32_e32 v115, v124, v164
	v_fmac_f32_e32 v113, v125, v127
	v_fmac_f32_e32 v115, v125, v165
	ds_read2_b32 v[124:125], v99 offset0:160 offset1:168
	ds_read2_b32 v[126:127], v101 offset0:112 offset1:120
	ds_read2_b32 v[164:165], v111 offset0:112 offset1:120
	ds_read2_b32 v[166:167], v99 offset0:176 offset1:184
	s_waitcnt lgkmcnt(4)
	v_fmac_f32_e32 v113, v102, v162
	v_fmac_f32_e32 v113, v103, v163
	s_waitcnt lgkmcnt(3)
	v_fmac_f32_e32 v115, v102, v124
	v_fmac_f32_e32 v115, v103, v125
	s_waitcnt lgkmcnt(1)
	v_fmac_f32_e32 v113, v126, v164
	s_waitcnt lgkmcnt(0)
	v_fmac_f32_e32 v115, v126, v166
	v_fmac_f32_e32 v113, v127, v165
	v_fmac_f32_e32 v115, v127, v167
	s_nop 1
	v_add_f32_dpp v113, v113, v113 quad_perm:[1,0,3,2] row_mask:0xf bank_mask:0xf
	v_add_f32_dpp v115, v115, v115 quad_perm:[1,0,3,2] row_mask:0xf bank_mask:0xf
	s_nop 0
	v_add_f32_dpp v113, v113, v113 quad_perm:[2,3,0,1] row_mask:0xf bank_mask:0xf
	v_add_f32_dpp v115, v115, v115 quad_perm:[2,3,0,1] row_mask:0xf bank_mask:0xf
	s_nop 0
	v_add_f32_dpp v113, v113, v113 row_half_mirror row_mask:0xf bank_mask:0xf
	v_add_f32_dpp v115, v115, v115 row_half_mirror row_mask:0xf bank_mask:0xf
	s_nop 0
	v_mov_b32_e32 v102, v113
	v_mov_b32_e32 v99, v115
	v_mov_b32_e32 v103, 0
	v_mov_b32_e32 v101, 0
	s_and_saveexec_b64 s[2:3], s[0:1]
	s_cbranch_execz .LBB0_1069
	v_cmp_ge_i32_e64 s[0:1], v158, v98
	v_mov_b32_e32 v104, 0
	v_lshl_add_u32 v113, v158, 2, 0
	v_mov_b32_e32 v111, 0
	s_and_saveexec_b64 s[14:15], s[0:1]
	s_cbranch_execz .LBB0_1066
	v_lshl_add_u32 v111, v98, 2, 0
	ds_read_b32 v115, v113 offset:47872
	ds_read_b32 v111, v111 offset:47872
	s_waitcnt lgkmcnt(0)
	v_sub_f32_e32 v111, v115, v111
	v_mul_f32_e32 v111, 0x3fb8aa3b, v111
	v_exp_f32_e32 v111, v111

.LBB0_1077:
	s_or_b64 exec, exec, s[2:3]
	v_readlane_b32 s40, v248, 29
	v_readlane_b32 s52, v248, 41
	v_readlane_b32 s53, v248, 42
	s_waitcnt lgkmcnt(0)
	s_barrier
	s_add_i32 s14, s22, s30
	s_waitcnt lgkmcnt(0)
	v_lshl_add_u64 v[98:99], v[102:103], 2, s[52:53]
	global_load_dword v115, v[98:99], off
	v_lshlrev_b32_e32 v98, 16, v147
	v_mul_f32_e32 v99, 0xbfb8aa3b, v98
	v_exp_f32_e32 v99, v99
	s_ashr_i32 s0, s14, 2
	s_and_b32 s12, s0, -8
	s_and_b32 s0, s23, 0xf80
	v_add_f32_e32 v99, 1.0, v99
	v_rcp_f32_e32 v99, v99
	s_addk_i32 s12, 0x2000
	s_lshl_b32 s0, s0, 1
	v_readlane_b32 s2, v247, 9
	v_readlane_b32 s3, v247, 10
	s_add_u32 s0, s2, s0
	s_addc_u32 s1, s3, 0
	v_lshl_add_u64 v[124:125], v[102:103], 1, s[0:1]
	v_mul_f32_e32 v103, v99, v98
	v_or_b32_e32 v98, s12, v97
	v_ashrrev_i32_e32 v99, 31, v98
	v_lshlrev_b64 v[98:99], 13, v[98:99]
	v_add_u32_e32 v97, 0xf000, v113
	v_lshl_add_u64 v[126:127], v[124:125], 0, v[98:99]
	ds_read2_b64 v[98:101], v97 offset1:4
	ds_read2_b64 v[164:167], v97 offset0:8 offset1:12
	ds_read2_b64 v[168:171], v97 offset0:16 offset1:20
	ds_read2_b64 v[172:175], v97 offset0:24 offset1:28
	s_brev_b32 s0, 60
	v_or_b32_e32 v96, s12, v96
	v_readlane_b32 s41, v248, 30
	v_readlane_b32 s42, v248, 31
	s_waitcnt lgkmcnt(3)
	v_pk_add_f32 v[98:99], v[98:99], 0 op_sel_hi:[1,0]
	v_readlane_b32 s43, v248, 32
	v_pk_add_f32 v[158:159], v[98:99], v[100:101]
	v_readlane_b32 s44, v248, 33
	v_readlane_b32 s45, v248, 34
	v_readlane_b32 s46, v248, 35
	v_readlane_b32 s47, v248, 36
	s_waitcnt lgkmcnt(2)
	v_pk_add_f32 v[98:99], v[158:159], v[164:165]
	v_readlane_b32 s48, v248, 37
	v_pk_add_f32 v[158:159], v[98:99], v[166:167]
	v_readlane_b32 s49, v248, 38
	v_readlane_b32 s50, v248, 39
	v_readlane_b32 s51, v248, 40
	v_readlane_b32 s54, v248, 43
	s_waitcnt lgkmcnt(1)
	v_pk_add_f32 v[98:99], v[158:159], v[168:169]
	v_readlane_b32 s55, v248, 44
	v_pk_add_f32 v[158:159], v[98:99], v[170:171]
	s_waitcnt lgkmcnt(0)
	v_pk_add_f32 v[98:99], v[158:159], v[172:173]
	s_nop 0
	v_pk_add_f32 v[98:99], v[98:99], v[174:175]
	v_mov_b32_e32 v100, 0
	v_pk_fma_f32 v[98:99], v[98:99], s[0:1], v[106:107] op_sel_hi:[1,0,0]
	s_nop 0
	v_mul_f32_e32 v97, 0x4b800000, v98
	v_cmp_gt_f32_e64 s[2:3], s29, v98
	v_cmp_gt_f32_e64 s[0:1], s29, v99
	s_nop 0
	v_cndmask_b32_e64 v97, v98, v97, s[2:3]
	v_rsq_f32_e32 v97, v97
	s_nop 0
	v_mul_f32_e32 v98, 0x45800000, v97
	v_cndmask_b32_e64 v97, v97, v98, s[2:3]
	v_mul_f32_e32 v97, v111, v97
	s_waitcnt vmcnt(0)
	v_mul_f32_e32 v97, v115, v97
	v_mul_f32_e32 v97, v103, v97
	v_cvt_pk_bf16_f32 v97, v97, s0
	global_store_short v[126:127], v97, off
	v_mul_f32_e32 v97, 0x4b800000, v99
	v_cndmask_b32_e64 v97, v99, v97, s[0:1]
	v_rsq_f32_e32 v97, v97
	s_nop 0
	v_mul_f32_e32 v98, 0x45800000, v97
	v_cndmask_b32_e64 v97, v97, v98, s[0:1]
	v_lshlrev_b32_e32 v98, 16, v146
	v_mul_f32_e32 v99, 0xbfb8aa3b, v98
	v_exp_f32_e32 v99, v99
	v_mul_f32_e32 v97, v104, v97
	v_mul_f32_e32 v97, v115, v97
	ds_read_b32 v104, v105 offset:47900
	v_add_f32_e32 v99, 1.0, v99
	v_rcp_f32_e32 v99, v99
	s_nop 0
	v_mul_f32_e32 v98, v99, v98
	v_mul_f32_e32 v97, v98, v97
	v_cvt_pk_bf16_f32 v98, v97, s0
	v_ashrrev_i32_e32 v97, 31, v96
	v_lshlrev_b64 v[96:97], 13, v[96:97]
	v_lshl_add_u64 v[96:97], v[124:125], 0, v[96:97]
	global_store_short v[96:97], v98, off
	v_mov_b32_e32 v96, 0
	v_mov_b32_e32 v97, 0
	v_mov_b32_e32 v98, 0
	v_mov_b32_e32 v99, 0
	v_lshlrev_b32_e32 v101, 3, v155
	v_lshl_add_u32 v146, v101, 1, 0
	v_mov_b32_e32 v164, 0
	v_mov_b32_e32 v165, 0
	v_mov_b32_e32 v166, 0
	v_mov_b32_e32 v167, 0
	v_mov_b32_e32 v168, 0
	v_mov_b32_e32 v169, 0
	v_mov_b32_e32 v170, 0
	v_mov_b32_e32 v171, 0
	v_mov_b32_e32 v172, 0
	v_mov_b32_e32 v173, 0
	v_mov_b32_e32 v174, 0
	v_mov_b32_e32 v175, 0
	v_mov_b32_e32 v176, 0
	v_mov_b32_e32 v177, 0
	v_mov_b32_e32 v178, 0
	v_mov_b32_e32 v179, 0
	v_mov_b32_e32 v192, 0
	v_mov_b32_e32 v193, 0
	v_mov_b32_e32 v194, 0
	v_mov_b32_e32 v195, 0
	v_mov_b32_e32 v196, 0
	v_mov_b32_e32 v197, 0
	v_mov_b32_e32 v198, 0
	v_mov_b32_e32 v199, 0
	v_mov_b32_e32 v234, 0
	v_mov_b32_e32 v235, 0
	v_mov_b32_e32 v236, 0
	v_mov_b32_e32 v237, 0
	v_mov_b32_e32 v238, 0
	v_mov_b32_e32 v239, 0
	v_mov_b32_e32 v240, 0
	v_mov_b32_e32 v241, 0
	s_and_saveexec_b64 s[0:1], vcc
	v_lshl_add_u32 v96, v102, 4, 0
	ds_read_b128 v[96:99], v96 offset:59392
	ds_read_b128 v[164:167], v146 offset:57344
	ds_read_b128 v[168:171], v146 offset:57600
	ds_read_b128 v[172:175], v146 offset:57856
	ds_read_b128 v[176:179], v146 offset:58112
	ds_read_b128 v[192:195], v146 offset:58368
	ds_read_b128 v[196:199], v146 offset:58624
	ds_read_b128 v[234:237], v146 offset:58880
	ds_read_b128 v[238:241], v146 offset:59136
	s_or_b64 exec, exec, s[0:1]
	s_waitcnt lgkmcnt(7)
	v_mul_f32_e32 v104, 0x3fb8aa3b, v104
	v_exp_f32_e32 v124, v104
	s_ashr_i32 s15, s14, 31
	s_lshl_b64 s[0:1], s[14:15], 16
	s_add_u32 s0, s20, s0
	v_pk_mul_f32 v[62:63], v[62:63], v[124:125] op_sel_hi:[1,0]
	v_pk_mul_f32 v[60:61], v[60:61], v[124:125] op_sel_hi:[1,0]
	s_addc_u32 s1, s21, s1
	v_lshl_add_u64 v[118:119], v[118:119], 2, s[0:1]
	v_mfma_f32_16x16x32_bf16 v[60:63], v[96:99], v[164:167], v[60:63]
	v_lshlrev_b32_e32 v104, 2, v154
	v_lshl_add_u64 v[118:119], v[118:119], 0, v[104:105]
	v_lshlrev_b32_e32 v104, 2, v156
	v_lshl_add_u64 v[100:101], v[118:119], 0, v[104:105]
	s_nop 2
	global_store_dwordx4 v[100:101], v[60:63], off
	v_mov_b32_e32 v125, v124
	v_mov_b32_e32 v126, v124
	v_mov_b32_e32 v127, v124
	v_pk_mul_f32 v[58:59], v[58:59], v[126:127]
	v_pk_mul_f32 v[56:57], v[56:57], v[124:125]
	v_mov_b32_e32 v123, v105
	v_lshl_add_u64 v[62:63], v[118:119], 0, v[122:123]
	s_waitcnt lgkmcnt(6)
	v_mfma_f32_16x16x32_bf16 v[56:59], v[96:99], v[168:171], v[56:59]
	s_nop 6
	global_store_dwordx4 v[62:63], v[56:59], off
	v_pk_mul_f32 v[54:55], v[54:55], v[126:127]
	v_pk_mul_f32 v[52:53], v[52:53], v[124:125]
	v_mov_b32_e32 v121, v105
	v_lshl_add_u64 v[56:57], v[118:119], 0, v[120:121]
	s_waitcnt lgkmcnt(5)
	v_mfma_f32_16x16x32_bf16 v[52:55], v[96:99], v[172:175], v[52:55]
	s_nop 7
	global_store_dwordx4 v[56:57], v[52:55], off
	v_mov_b32_e32 v58, v124
	v_mov_b32_e32 v59, v124
	v_pk_mul_f32 v[50:51], v[50:51], v[58:59]
	v_pk_mul_f32 v[48:49], v[48:49], v[124:125]
	v_mov_b32_e32 v117, v105
	s_waitcnt lgkmcnt(4)
	v_mfma_f32_16x16x32_bf16 v[48:51], v[96:99], v[176:179], v[48:51]
	v_lshl_add_u64 v[54:55], v[118:119], 0, v[116:117]
	s_nop 6
	global_store_dwordx4 v[54:55], v[48:51], off
	v_pk_mul_f32 v[46:47], v[46:47], v[58:59]
	v_pk_mul_f32 v[44:45], v[44:45], v[124:125]
	v_mov_b32_e32 v115, v105
	v_lshl_add_u64 v[48:49], v[118:119], 0, v[114:115]
	s_waitcnt lgkmcnt(3)
	v_mfma_f32_16x16x32_bf16 v[44:47], v[96:99], v[192:195], v[44:47]
	s_nop 7
	global_store_dwordx4 v[48:49], v[44:47], off
	v_mov_b32_e32 v50, v124
	v_mov_b32_e32 v51, v124
	v_pk_mul_f32 v[42:43], v[42:43], v[50:51]
	v_pk_mul_f32 v[40:41], v[40:41], v[124:125]
	v_mov_b32_e32 v113, v105
	s_waitcnt lgkmcnt(2)
	v_mfma_f32_16x16x32_bf16 v[40:43], v[96:99], v[196:199], v[40:43]
	v_lshl_add_u64 v[46:47], v[118:119], 0, v[112:113]
	s_nop 6
	global_store_dwordx4 v[46:47], v[40:43], off
	v_pk_mul_f32 v[38:39], v[38:39], v[50:51]
	v_pk_mul_f32 v[36:37], v[36:37], v[124:125]
	v_mov_b32_e32 v111, v105
	v_lshl_add_u64 v[40:41], v[118:119], 0, v[110:111]
	s_waitcnt lgkmcnt(1)
	v_mfma_f32_16x16x32_bf16 v[36:39], v[96:99], v[234:237], v[36:39]
	s_nop 7
	global_store_dwordx4 v[40:41], v[36:39], off
	s_nop 1
	v_mov_b32_e32 v40, v124
	v_mov_b32_e32 v41, v124
	v_pk_mul_f32 v[34:35], v[34:35], v[40:41]
	v_pk_mul_f32 v[32:33], v[32:33], v[124:125]
	v_and_b32_e32 v147, 0xffff, v109
	v_mov_b32_e32 v109, v105
	s_waitcnt lgkmcnt(0)
	v_mfma_f32_16x16x32_bf16 v[32:35], v[96:99], v[238:241], v[32:35]
	v_lshl_add_u64 v[36:37], v[118:119], 0, v[108:109]
	s_add_i32 s30, s30, s18
	s_add_i32 s23, s23, s24
	s_add_i32 s26, s26, -1
	v_and_b32_e32 v146, 0xffff, v157
	s_nop 2
	global_store_dwordx4 v[36:37], v[32:35], off
	s_waitcnt lgkmcnt(0)
	s_barrier
	s_cmp_eq_u32 s26, 0
	s_cbranch_scc1 .LBB0_1098
	v_mov_b64_e32 v[32:33], v[64:65]
	v_mov_b64_e32 v[36:37], v[68:69]
	v_mov_b64_e32 v[40:41], v[72:73]
	v_mov_b64_e32 v[44:45], v[76:77]
	v_mov_b64_e32 v[48:49], v[80:81]
	v_mov_b64_e32 v[52:53], v[84:85]
	v_mov_b64_e32 v[56:57], v[88:89]
	v_mov_b64_e32 v[60:61], v[92:93]
	v_mov_b64_e32 v[34:35], v[66:67]
	v_mov_b64_e32 v[38:39], v[70:71]
	v_mov_b64_e32 v[42:43], v[74:75]
	v_mov_b64_e32 v[46:47], v[78:79]
	v_mov_b64_e32 v[50:51], v[82:83]
	v_mov_b64_e32 v[54:55], v[86:87]
	v_mov_b64_e32 v[58:59], v[90:91]
	v_mov_b64_e32 v[62:63], v[94:95]
	s_branch .LBB0_1058
